# RWKV phase: helper waves raised to priority 2 (they are the longer pole of a chunk)
# baseline (speedup 1.0000x reference)
.LBB0_391:
	s_andn2_b64 vcc, exec, s[36:37]
	s_cbranch_vccnz .LBB0_411
	s_setprio 2
	s_cmp_lg_u32 s2, 0
	s_cbranch_scc1 .Lcm_done
	v_and_b32_e32 v216, 48, v98
	v_add_u32_e32 v217, v145, v216
	v_lshl_add_u32 v218, v216, 1, v217
	ds_read_b128 v[220:223], v217 offset:16640
	ds_read_b128 v[224:227], v217 offset:16656
	ds_read_b128 v[228:231], v217 offset:16768
	ds_read_b128 v[244:247], v217 offset:16784
	s_mov_b32 s8, 0xffff0000
	s_waitcnt lgkmcnt(0)
	v_and_b32_e32 v219, 0xffff, v220
	v_lshl_or_b32 v248, v228, 16, v219
	v_lshrrev_b32_e32 v219, 16, v220
	v_and_or_b32 v249, v228, s8, v219
	v_and_b32_e32 v219, 0xffff, v221
	v_lshl_or_b32 v250, v229, 16, v219
	v_lshrrev_b32_e32 v219, 16, v221
	v_and_or_b32 v251, v229, s8, v219
	ds_write_b128 v218, v[248:251] offset:16640
	v_and_b32_e32 v219, 0xffff, v222
	v_lshl_or_b32 v92, v230, 16, v219
	v_lshrrev_b32_e32 v219, 16, v222
	v_and_or_b32 v93, v230, s8, v219
	v_and_b32_e32 v219, 0xffff, v223
	v_lshl_or_b32 v94, v231, 16, v219
	v_lshrrev_b32_e32 v219, 16, v223
	v_and_or_b32 v95, v231, s8, v219
	ds_write_b128 v218, v[92:95] offset:16656
	v_and_b32_e32 v219, 0xffff, v224
	v_lshl_or_b32 v248, v244, 16, v219
	v_lshrrev_b32_e32 v219, 16, v224
	v_and_or_b32 v249, v244, s8, v219
	v_and_b32_e32 v219, 0xffff, v225
	v_lshl_or_b32 v250, v245, 16, v219
	v_lshrrev_b32_e32 v219, 16, v225
	v_and_or_b32 v251, v245, s8, v219
	ds_write_b128 v218, v[248:251] offset:16672
	v_and_b32_e32 v219, 0xffff, v226
	v_lshl_or_b32 v92, v246, 16, v219
	v_lshrrev_b32_e32 v219, 16, v226
	v_and_or_b32 v93, v246, s8, v219
	v_and_b32_e32 v219, 0xffff, v227
	v_lshl_or_b32 v94, v247, 16, v219
	v_lshrrev_b32_e32 v219, 16, v227
	v_and_or_b32 v95, v247, s8, v219
	ds_write_b128 v218, v[92:95] offset:16688
	s_waitcnt lgkmcnt(0)
